# FFN-up epilogue: the 8 conv-weight/bias global loads hoisted to the epilogue start (saddr form), ahead of the rs scaling and the two halo barriers
# speedup vs baseline: 1.0343x; 1.0138x over previous
; #define PG8_STAGE(bufoff, gbase, voff) do { _Pragma("unroll") for (int _i = 0; _i < 2; ++_i) \
;         __builtin_amdgcn_global_load_lds((const unsigned*)((const char*)(gbase) + (voff)[_i]), (LAS unsigned*)(lds + (bufoff) + ldsw + _i * 8192), 16, 0, 0); } while (0)
; #define PG8_LDA(dst, b, h) do { _Pragma("unroll") for (int m = 0; m < 4; ++m) _Pragma("unroll") for (int k = 0; k < 2; ++k) dst[m][k] = *(const LAS bf16x8*)(lds + PG8_SA(b, h) + aoff + m * 2048 + k * 1024); } while (0)
; #define PG8_LDB(dst, b, h) do { _Pragma("unroll") for (int n = 0; n < 2; ++n) _Pragma("unroll") for (int k = 0; k < 2; ++k) dst[n][k] = *(const LAS bf16x8*)(lds + PG8_SB(b, h) + boff + n * 2048 + k * 1024); } while (0)
; #define PG8_MMA(ai, bj, At, Bt) do { __builtin_amdgcn_s_setprio(1); _Pragma("unroll") for (int m = 0; m < 4; ++m) _Pragma("unroll") for (int n = 0; n < 2; ++n) _Pragma("unroll") for (int k = 0; k < 2; ++k) \
;         acc[ai][bj][m][n] = __builtin_amdgcn_mfma_f32_16x16x32_bf16(Bt[n][k], At[m][k], acc[ai][bj][m][n], 0, 0, 0); __builtin_amdgcn_s_setprio(0); } while (0)
; #define PG8_WAIT_V(n) asm volatile("s_waitcnt vmcnt(" #n ")" ::: "memory")
; #define PG8_BAR __builtin_amdgcn_s_barrier()
; template <class Epi, class Sched>
; __device__ __forceinline__ void gemm_phase(LAS unsigned char* lds, const Gemm g, const Sched& S, const Epi& E) {
;     ...
;         for (int t = 0; t < nt; t += 2) {
;             const bool last = (t == nt - 2);
;             const char* a1 = cA + (size_t)(t + 1) * kstep;
;             const char* a2 = last ? nA : cA + (size_t)(t + 2) * kstep; const char* b2 = last ? nB : cB + (size_t)(t + 2) * kstep;
;             const char* a3 = a2 + kstep; const char* b3 = b2 + kstep;
;             if (last && has_next) S.a_ready(nxt);
;             PG8_LDB(B0, 0, 0); PG8_SCHED; PG8_LDA(At, 0, 0); PG8_STAGE(PG8_SA(1, 1), a1 + hstepA, voffA);
;             PG8_WAIT_L(8); PG8_BAR; PG8_WAIT_L(0); PG8_MMA(0, 0, At, B0); PG8_BAR; PG8_SCHED;
;             PG8_LDB(B1, 0, 1); PG8_STAGE(PG8_SB(0, 0), b2, voffB);
;             PG8_BAR; PG8_WAIT_L(0); PG8_MMA(0, 1, At, B1); PG8_BAR;
;             PG8_LDA(At, 0, 1); PG8_STAGE(PG8_SA(0, 0), a2, voffA);
;             PG8_BAR; PG8_WAIT_L(0); PG8_MMA(1, 0, At, B0); PG8_BAR; PG8_SCHED;
;             PG8_STAGE(PG8_SB(0, 1), b2 + hstepB, voffB);
;             PG8_WAIT_V(6); PG8_BAR; PG8_MMA(1, 1, At, B1); PG8_BAR;
.LBB0_1526:
	s_setprio 0
	s_add_u32 s6, s4, 0xfff80080
	s_addc_u32 s7, s5, -1
	s_add_i32 s72, 0, 0x10000
	v_add_u32_e32 v2, s72, v1
	ds_read_b128 v[132:135], v2
	ds_read_b128 v[136:139], v2 offset:1024
	ds_read_b128 v[140:143], v2 offset:2048
	ds_read_b128 v[144:147], v2 offset:3072
	s_cmp_eq_u32 s71, 28
	s_cselect_b32 s15, s57, s7
	s_cselect_b32 s14, s67, s6
	s_cselect_b32 s7, s55, s70
	s_cselect_b32 s6, s68, s69
	ds_read_b128 v[148:151], v207
	ds_read_b128 v[152:155], v207 offset:1024
	ds_read_b128 v[156:159], v207 offset:2048
	ds_read_b128 v[160:163], v207 offset:3072
	ds_read_b128 v[164:167], v207 offset:4096
	ds_read_b128 v[168:171], v207 offset:5120
	ds_read_b128 v[186:189], v207 offset:6144
	ds_read_b128 v[190:193], v207 offset:7168
	s_add_i32 s74, 0, 0x14000
	v_add_u32_e32 v2, s74, v1
	ds_read_b128 v[194:197], v2
	ds_read_b128 v[198:201], v2 offset:1024
	ds_read_b128 v[202:205], v2 offset:2048
	ds_read_b128 v[208:211], v2 offset:3072
	s_add_i32 m0, s20, 0xc000
	s_nop 0
	global_load_lds_dwordx4 v182, s[4:5]
	s_add_i32 m0, s20, 0xe000
	s_nop 0
	global_load_lds_dwordx4 v184, s[4:5]
	s_waitcnt lgkmcnt(0)
	s_setprio 1
	s_barrier
	v_mfma_f32_16x16x32_bf16 v[68:71], v[132:135], v[148:151], v[68:71]
	v_mfma_f32_16x16x32_bf16 v[72:75], v[140:143], v[148:151], v[72:75]
	v_mfma_f32_16x16x32_bf16 v[120:123], v[132:135], v[156:159], v[120:123]
	v_mfma_f32_16x16x32_bf16 v[116:119], v[140:143], v[156:159], v[116:119]
	v_mfma_f32_16x16x32_bf16 v[112:115], v[132:135], v[164:167], v[112:115]
	v_mfma_f32_16x16x32_bf16 v[108:111], v[140:143], v[164:167], v[108:111]
	v_mfma_f32_16x16x32_bf16 v[104:107], v[132:135], v[186:189], v[104:107]
	v_mfma_f32_16x16x32_bf16 v[100:103], v[140:143], v[186:189], v[100:103]
	v_mfma_f32_16x16x32_bf16 v[68:71], v[136:139], v[152:155], v[68:71]
	v_mfma_f32_16x16x32_bf16 v[72:75], v[144:147], v[152:155], v[72:75]
	v_mfma_f32_16x16x32_bf16 v[120:123], v[136:139], v[160:163], v[120:123]
	v_mfma_f32_16x16x32_bf16 v[116:119], v[144:147], v[160:163], v[116:119]
	v_mfma_f32_16x16x32_bf16 v[112:115], v[136:139], v[168:171], v[112:115]
	v_mfma_f32_16x16x32_bf16 v[108:111], v[144:147], v[168:171], v[108:111]
	v_mfma_f32_16x16x32_bf16 v[104:107], v[136:139], v[190:193], v[104:107]
	v_mfma_f32_16x16x32_bf16 v[100:103], v[144:147], v[190:193], v[100:103]
	v_mfma_f32_16x16x32_bf16 v[76:79], v[194:197], v[148:151], v[76:79]
	v_mfma_f32_16x16x32_bf16 v[80:83], v[202:205], v[148:151], v[80:83]
	v_mfma_f32_16x16x32_bf16 v[96:99], v[194:197], v[156:159], v[96:99]
	v_mfma_f32_16x16x32_bf16 v[92:95], v[202:205], v[156:159], v[92:95]
	v_mfma_f32_16x16x32_bf16 v[88:91], v[194:197], v[164:167], v[88:91]
	v_mfma_f32_16x16x32_bf16 v[84:87], v[202:205], v[164:167], v[84:87]
	v_mfma_f32_16x16x32_bf16 v[128:131], v[194:197], v[186:189], v[128:131]
	v_mfma_f32_16x16x32_bf16 v[124:127], v[202:205], v[186:189], v[124:127]
	v_mfma_f32_16x16x32_bf16 v[76:79], v[198:201], v[152:155], v[76:79]
	v_mfma_f32_16x16x32_bf16 v[80:83], v[208:211], v[152:155], v[80:83]
	v_mfma_f32_16x16x32_bf16 v[96:99], v[198:201], v[160:163], v[96:99]
	v_mfma_f32_16x16x32_bf16 v[92:95], v[208:211], v[160:163], v[92:95]
	v_mfma_f32_16x16x32_bf16 v[88:91], v[198:201], v[168:171], v[88:91]
	v_mfma_f32_16x16x32_bf16 v[84:87], v[208:211], v[168:171], v[84:87]
	v_mfma_f32_16x16x32_bf16 v[128:131], v[198:201], v[190:193], v[128:131]
	v_mfma_f32_16x16x32_bf16 v[124:127], v[208:211], v[190:193], v[124:127]
	s_barrier
	s_setprio 0
	ds_read_b128 v[148:151], v207 offset:16384
	ds_read_b128 v[152:155], v207 offset:17408
	ds_read_b128 v[156:159], v207 offset:18432
	ds_read_b128 v[160:163], v207 offset:19456
	ds_read_b128 v[164:167], v207 offset:20480
	ds_read_b128 v[168:171], v207 offset:21504
	ds_read_b128 v[186:189], v207 offset:22528
	ds_read_b128 v[190:193], v207 offset:23552
	s_add_i32 s72, s72, s19
	v_lshl_add_u64 v[172:173], s[6:7], 0, v[178:179]
	s_mov_b32 m0, s72
	s_nop 0
	global_load_lds_dwordx4 v[172:173], off
	v_lshl_add_u64 v[212:213], s[6:7], 0, v[174:175]
	s_add_i32 m0, s72, 0x2000
	s_nop 0
	global_load_lds_dwordx4 v[212:213], off
	s_mov_b32 m0, s20
	v_lshl_add_u64 v[216:217], s[14:15], 0, v[180:181]
	global_load_lds_dwordx4 v[216:217], off
	v_lshl_add_u64 v[218:219], s[14:15], 0, v[176:177]
	s_mov_b32 m0, s21
	s_nop 0
	global_load_lds_dwordx4 v[218:219], off
	s_add_u32 s72, s6, 0x80000
	s_addc_u32 s73, s7, 0
	s_add_i32 s74, s74, s19
	s_mov_b32 m0, s74
	s_nop 0
	global_load_lds_dwordx4 v178, s[72:73]
	s_add_i32 m0, s74, 0x2000
	s_nop 0
	global_load_lds_dwordx4 v174, s[72:73]
	s_waitcnt lgkmcnt(0)
	s_waitcnt vmcnt(6)
	s_setprio 1
	s_barrier
; #define PG8_STAGE(bufoff, gbase, voff) do { _Pragma("unroll") for (int _i = 0; _i < 2; ++_i) \
;         __builtin_amdgcn_global_load_lds((const unsigned*)((const char*)(gbase) + (voff)[_i]), (LAS unsigned*)(lds + (bufoff) + ldsw + _i * 8192), 16, 0, 0); } while (0)
; #define PG8_LDA(dst, b, h) do { _Pragma("unroll") for (int m = 0; m < 4; ++m) _Pragma("unroll") for (int k = 0; k < 2; ++k) dst[m][k] = *(const LAS bf16x8*)(lds + PG8_SA(b, h) + aoff + m * 2048 + k * 1024); } while (0)
; #define PG8_LDB(dst, b, h) do { _Pragma("unroll") for (int n = 0; n < 2; ++n) _Pragma("unroll") for (int k = 0; k < 2; ++k) dst[n][k] = *(const LAS bf16x8*)(lds + PG8_SB(b, h) + boff + n * 2048 + k * 1024); } while (0)
; #define PG8_MMA(ai, bj, At, Bt) do { __builtin_amdgcn_s_setprio(1); _Pragma("unroll") for (int m = 0; m < 4; ++m) _Pragma("unroll") for (int n = 0; n < 2; ++n) _Pragma("unroll") for (int k = 0; k < 2; ++k) \
;         acc[ai][bj][m][n] = __builtin_amdgcn_mfma_f32_16x16x32_bf16(Bt[n][k], At[m][k], acc[ai][bj][m][n], 0, 0, 0); __builtin_amdgcn_s_setprio(0); } while (0)
; #define PG8_WAIT_V(n) asm volatile("s_waitcnt vmcnt(" #n ")" ::: "memory")
; #define PG8_WAIT_L(n) asm volatile("s_waitcnt lgkmcnt(" #n ")" ::: "memory")
; #define PG8_BAR __builtin_amdgcn_s_barrier()
; #define PG8_SCHED __builtin_amdgcn_sched_barrier(0)
; template <class Epi, class Sched>
; __device__ __forceinline__ void gemm_phase(LAS unsigned char* lds, const Gemm g, const Sched& S, const Epi& E) {
;     ...
;             PG8_WAIT_V(6); PG8_BAR; PG8_MMA(1, 1, At, B1); PG8_BAR;
;             PG8_LDB(B0, 1, 0); PG8_SCHED; PG8_LDA(At, 1, 0); PG8_STAGE(PG8_SA(0, 1), a2 + hstepA, voffA);
;             PG8_WAIT_L(8); PG8_BAR; PG8_WAIT_L(0); PG8_MMA(0, 0, At, B0); PG8_BAR; PG8_SCHED;
;             PG8_LDB(B1, 1, 1); PG8_STAGE(PG8_SB(1, 0), b3, voffB);
;             PG8_BAR; PG8_WAIT_L(0); PG8_MMA(0, 1, At, B1); PG8_BAR;
;             PG8_LDA(At, 1, 1); PG8_STAGE(PG8_SA(1, 0), a3, voffA);
;             PG8_BAR; PG8_WAIT_L(0); PG8_MMA(1, 0, At, B0); PG8_BAR; PG8_SCHED;
	v_mfma_f32_16x16x32_bf16 v[56:59], v[132:135], v[148:151], v[56:59]
	v_mfma_f32_16x16x32_bf16 v[52:55], v[140:143], v[148:151], v[52:55]
	v_mfma_f32_16x16x32_bf16 v[48:51], v[132:135], v[156:159], v[48:51]
	v_mfma_f32_16x16x32_bf16 v[44:47], v[140:143], v[156:159], v[44:47]
	v_mfma_f32_16x16x32_bf16 v[40:43], v[132:135], v[164:167], v[40:43]
	v_mfma_f32_16x16x32_bf16 v[36:39], v[140:143], v[164:167], v[36:39]
	v_mfma_f32_16x16x32_bf16 v[32:35], v[132:135], v[186:189], v[32:35]
	v_mfma_f32_16x16x32_bf16 v[28:31], v[140:143], v[186:189], v[28:31]
	v_mfma_f32_16x16x32_bf16 v[56:59], v[136:139], v[152:155], v[56:59]
	v_mfma_f32_16x16x32_bf16 v[52:55], v[144:147], v[152:155], v[52:55]
	v_mfma_f32_16x16x32_bf16 v[48:51], v[136:139], v[160:163], v[48:51]
	v_mfma_f32_16x16x32_bf16 v[44:47], v[144:147], v[160:163], v[44:47]
	v_mfma_f32_16x16x32_bf16 v[40:43], v[136:139], v[168:171], v[40:43]
	v_mfma_f32_16x16x32_bf16 v[36:39], v[144:147], v[168:171], v[36:39]
	v_mfma_f32_16x16x32_bf16 v[32:35], v[136:139], v[190:193], v[32:35]
	v_mfma_f32_16x16x32_bf16 v[28:31], v[144:147], v[190:193], v[28:31]
	v_mfma_f32_16x16x32_bf16 v[24:27], v[194:197], v[148:151], v[24:27]
	v_mfma_f32_16x16x32_bf16 v[20:23], v[202:205], v[148:151], v[20:23]
	v_mfma_f32_16x16x32_bf16 v[16:19], v[194:197], v[156:159], v[16:19]
	v_mfma_f32_16x16x32_bf16 v[12:15], v[202:205], v[156:159], v[12:15]
	v_mfma_f32_16x16x32_bf16 v[8:11], v[194:197], v[164:167], v[8:11]
	v_mfma_f32_16x16x32_bf16 v[4:7], v[202:205], v[164:167], v[4:7]
	v_mfma_f32_16x16x32_bf16 v[60:63], v[194:197], v[186:189], v[60:63]
	v_mfma_f32_16x16x32_bf16 v[64:67], v[202:205], v[186:189], v[64:67]
	v_mfma_f32_16x16x32_bf16 v[24:27], v[198:201], v[152:155], v[24:27]
	v_mfma_f32_16x16x32_bf16 v[20:23], v[208:211], v[152:155], v[20:23]
	v_mfma_f32_16x16x32_bf16 v[16:19], v[198:201], v[160:163], v[16:19]
	v_mfma_f32_16x16x32_bf16 v[12:15], v[208:211], v[160:163], v[12:15]
	v_mfma_f32_16x16x32_bf16 v[8:11], v[198:201], v[168:171], v[8:11]
	v_mfma_f32_16x16x32_bf16 v[4:7], v[208:211], v[168:171], v[4:7]
	v_mfma_f32_16x16x32_bf16 v[60:63], v[198:201], v[190:193], v[60:63]
	v_mfma_f32_16x16x32_bf16 v[64:67], v[208:211], v[190:193], v[64:67]
	s_barrier
	s_setprio 0
	s_add_i32 s72, 0, 0x18000
	v_add_u32_e32 v2, s72, v1
	ds_read_b128 v[132:135], v2
	ds_read_b128 v[136:139], v2 offset:1024
	ds_read_b128 v[140:143], v2 offset:2048
	ds_read_b128 v[144:147], v2 offset:3072
	s_add_u32 s14, s14, 0x80000
	s_addc_u32 s15, s15, 0
	ds_read_b128 v[148:151], v207 offset:32768
	ds_read_b128 v[152:155], v207 offset:33792
	ds_read_b128 v[156:159], v207 offset:34816
	ds_read_b128 v[160:163], v207 offset:35840
	ds_read_b128 v[164:167], v207 offset:36864
	ds_read_b128 v[168:171], v207 offset:37888
	ds_read_b128 v[186:189], v207 offset:38912
	ds_read_b128 v[190:193], v207 offset:39936
	s_mov_b32 m0, s24
	s_nop 0
	global_load_lds_dwordx4 v180, s[14:15]
	s_mov_b32 m0, s25
	s_nop 0
	global_load_lds_dwordx4 v176, s[14:15]
	s_add_i32 s14, 0, 0x1c000
	v_add_u32_e32 v2, s14, v1
	ds_read_b128 v[194:197], v2
	ds_read_b128 v[198:201], v2 offset:1024
	ds_read_b128 v[202:205], v2 offset:2048
	ds_read_b128 v[208:211], v2 offset:3072
	s_waitcnt lgkmcnt(0)
	s_setprio 1
	s_barrier
	v_mfma_f32_16x16x32_bf16 v[68:71], v[132:135], v[148:151], v[68:71]
	v_mfma_f32_16x16x32_bf16 v[72:75], v[140:143], v[148:151], v[72:75]
	v_mfma_f32_16x16x32_bf16 v[120:123], v[132:135], v[156:159], v[120:123]
	v_mfma_f32_16x16x32_bf16 v[116:119], v[140:143], v[156:159], v[116:119]
	v_mfma_f32_16x16x32_bf16 v[112:115], v[132:135], v[164:167], v[112:115]
	v_mfma_f32_16x16x32_bf16 v[108:111], v[140:143], v[164:167], v[108:111]
	v_mfma_f32_16x16x32_bf16 v[104:107], v[132:135], v[186:189], v[104:107]
	v_mfma_f32_16x16x32_bf16 v[100:103], v[140:143], v[186:189], v[100:103]
	v_mfma_f32_16x16x32_bf16 v[68:71], v[136:139], v[152:155], v[68:71]
	v_mfma_f32_16x16x32_bf16 v[72:75], v[144:147], v[152:155], v[72:75]
	v_mfma_f32_16x16x32_bf16 v[120:123], v[136:139], v[160:163], v[120:123]
	v_mfma_f32_16x16x32_bf16 v[116:119], v[144:147], v[160:163], v[116:119]
	v_mfma_f32_16x16x32_bf16 v[112:115], v[136:139], v[168:171], v[112:115]
	v_mfma_f32_16x16x32_bf16 v[108:111], v[144:147], v[168:171], v[108:111]
	v_mfma_f32_16x16x32_bf16 v[104:107], v[136:139], v[190:193], v[104:107]
	v_mfma_f32_16x16x32_bf16 v[100:103], v[144:147], v[190:193], v[100:103]
	v_mfma_f32_16x16x32_bf16 v[76:79], v[194:197], v[148:151], v[76:79]
	v_mfma_f32_16x16x32_bf16 v[80:83], v[202:205], v[148:151], v[80:83]
	v_mfma_f32_16x16x32_bf16 v[96:99], v[194:197], v[156:159], v[96:99]
	v_mfma_f32_16x16x32_bf16 v[92:95], v[202:205], v[156:159], v[92:95]
	v_mfma_f32_16x16x32_bf16 v[88:91], v[194:197], v[164:167], v[88:91]
	v_mfma_f32_16x16x32_bf16 v[84:87], v[202:205], v[164:167], v[84:87]
	v_mfma_f32_16x16x32_bf16 v[128:131], v[194:197], v[186:189], v[128:131]
	v_mfma_f32_16x16x32_bf16 v[124:127], v[202:205], v[186:189], v[124:127]
	v_mfma_f32_16x16x32_bf16 v[76:79], v[198:201], v[152:155], v[76:79]
	v_mfma_f32_16x16x32_bf16 v[80:83], v[208:211], v[152:155], v[80:83]
	v_mfma_f32_16x16x32_bf16 v[96:99], v[198:201], v[160:163], v[96:99]
	v_mfma_f32_16x16x32_bf16 v[92:95], v[208:211], v[160:163], v[92:95]
	v_mfma_f32_16x16x32_bf16 v[88:91], v[198:201], v[168:171], v[88:91]
	v_mfma_f32_16x16x32_bf16 v[84:87], v[208:211], v[168:171], v[84:87]
	v_mfma_f32_16x16x32_bf16 v[128:131], v[198:201], v[190:193], v[128:131]
	v_mfma_f32_16x16x32_bf16 v[124:127], v[208:211], v[190:193], v[124:127]
	s_barrier
; #define LAS __attribute__((address_space(3)))
; __device__ __forceinline__ int opaque_tid() { int t = threadIdx.x; asm volatile("" : "+v"(t)); return t; }
; #define PG8_STAGE(bufoff, gbase, voff) do { _Pragma("unroll") for (int _i = 0; _i < 2; ++_i) \
;         __builtin_amdgcn_global_load_lds((const unsigned*)((const char*)(gbase) + (voff)[_i]), (LAS unsigned*)(lds + (bufoff) + ldsw + _i * 8192), 16, 0, 0); } while (0)
; #define PG8_WAIT_V(n) asm volatile("s_waitcnt vmcnt(" #n ")" ::: "memory")
; #define PG8_WAIT_L(n) asm volatile("s_waitcnt lgkmcnt(" #n ")" ::: "memory")
;     __device__ __forceinline__ void operator()(f32x4 (&acc)[2][2][4][2], const Unit& u, int wr, int wc, int ui, int) const {
;         const int ol_ = opaque_tid() & 63, fr = ol_ & 15, fq = ol_ >> 4;
;         { float r_[2][4];
;           rs_read(r_, ui, wr, fr);
; #pragma unroll
;           for (int ai = 0; ai < 2; ++ai)
; #pragma unroll
;               for (int bj = 0; bj < 2; ++bj)
; #pragma unroll
;                   for (int m = 0; m < 4; ++m) { acc[ai][bj][m][0] *= r_[ai][m]; acc[ai][bj][m][1] *= r_[ai][m]; } }
;         const int col = u.pn * 128 + wc * 32 + 8 * fq;
;         if (fr >= 14) {
; #pragma unroll
;             for (int ai = 0; ai < 2; ++ai) { LAS f32x4* s = (LAS f32x4*)(hl + ((((ai * 2 + wr) * 4 + wc) * 8 + fq * 2 + (fr - 14)) * 32));
;                 s[0] = acc[ai][1][3][0]; s[1] = acc[ai][1][3][1]; }
;         }
;         asm volatile("s_waitcnt lgkmcnt(0)" ::: "memory"); __builtin_amdgcn_s_barrier(); asm volatile("" ::: "memory");
;         __builtin_amdgcn_s_barrier(); asm volatile("" ::: "memory");
;         float w0[8], w1[8], w2[8], bb[8];
;         { const f32x4 a0 = *(const f32x4*)(cw + col), a1 = *(const f32x4*)(cw + col + 4), b0 = *(const f32x4*)(cw + FF + col), b1 = *(const f32x4*)(cw + FF + col + 4),
;                       c0 = *(const f32x4*)(cw + 2 * FF + col), c1 = *(const f32x4*)(cw + 2 * FF + col + 4), d0 = *(const f32x4*)(cb + col), d1 = *(const f32x4*)(cb + col + 4);
; template <class Epi, class Sched>
; __device__ __forceinline__ void gemm_phase(LAS unsigned char* lds, const Gemm g, const Sched& S, const Epi& E) {
;     ...
;             PG8_BAR; PG8_WAIT_L(0); PG8_MMA(1, 0, At, B0); PG8_BAR; PG8_SCHED;
;             PG8_STAGE(PG8_SB(1, 1), b3 + hstepB, voffB);
;             PG8_WAIT_V(6); PG8_BAR; PG8_MMA(1, 1, At, B1); PG8_BAR;
	s_setprio 0
	ds_read_b128 v[148:151], v207 offset:49152
	ds_read_b128 v[152:155], v207 offset:50176
	ds_read_b128 v[156:159], v207 offset:51200
	ds_read_b128 v[160:163], v207 offset:52224
	ds_read_b128 v[164:167], v207 offset:53248
	ds_read_b128 v[168:171], v207 offset:54272
	ds_read_b128 v[186:189], v207 offset:55296
	ds_read_b128 v[190:193], v207 offset:56320
	s_add_i32 s15, s72, s19
	v_lshl_add_u64 v[172:173], v[172:173], 0, s[8:9]
	s_mov_b32 m0, s15
	s_nop 0
	global_load_lds_dwordx4 v[172:173], off
	v_lshl_add_u64 v[172:173], v[212:213], 0, s[8:9]
	s_add_i32 m0, s15, 0x2000
	s_nop 0
	global_load_lds_dwordx4 v[172:173], off
	s_mov_b32 m0, s30
	v_lshl_add_u64 v[172:173], v[216:217], 0, s[8:9]
	global_load_lds_dwordx4 v[172:173], off
	v_lshl_add_u64 v[172:173], v[218:219], 0, s[8:9]
	s_mov_b32 m0, s31
	s_nop 0
	global_load_lds_dwordx4 v[172:173], off
	s_add_u32 s6, s6, 0x80080
	s_addc_u32 s7, s7, 0
	s_add_i32 s14, s14, s19
	s_mov_b32 m0, s14
	s_nop 0
	global_load_lds_dwordx4 v178, s[6:7]
	s_add_i32 m0, s14, 0x2000
	s_nop 0
	global_load_lds_dwordx4 v174, s[6:7]
	s_add_i32 s71, s71, 2
	s_add_u32 s4, s4, 0x100
	s_addc_u32 s5, s5, 0
	s_add_u32 s69, s69, 0x100
	s_addc_u32 s70, s70, 0
	s_cmp_gt_u32 s71, 29
	s_waitcnt lgkmcnt(0)
	s_waitcnt vmcnt(6)
	s_setprio 1
	s_barrier
	v_mfma_f32_16x16x32_bf16 v[56:59], v[132:135], v[148:151], v[56:59]
	v_mfma_f32_16x16x32_bf16 v[52:55], v[140:143], v[148:151], v[52:55]
	v_mfma_f32_16x16x32_bf16 v[48:51], v[132:135], v[156:159], v[48:51]
	v_mfma_f32_16x16x32_bf16 v[44:47], v[140:143], v[156:159], v[44:47]
	v_mfma_f32_16x16x32_bf16 v[40:43], v[132:135], v[164:167], v[40:43]
	v_mfma_f32_16x16x32_bf16 v[36:39], v[140:143], v[164:167], v[36:39]
	v_mfma_f32_16x16x32_bf16 v[32:35], v[132:135], v[186:189], v[32:35]
	v_mfma_f32_16x16x32_bf16 v[28:31], v[140:143], v[186:189], v[28:31]
	v_mfma_f32_16x16x32_bf16 v[56:59], v[136:139], v[152:155], v[56:59]
	v_mfma_f32_16x16x32_bf16 v[52:55], v[144:147], v[152:155], v[52:55]
	v_mfma_f32_16x16x32_bf16 v[48:51], v[136:139], v[160:163], v[48:51]
	v_mfma_f32_16x16x32_bf16 v[44:47], v[144:147], v[160:163], v[44:47]
	v_mfma_f32_16x16x32_bf16 v[40:43], v[136:139], v[168:171], v[40:43]
	v_mfma_f32_16x16x32_bf16 v[36:39], v[144:147], v[168:171], v[36:39]
	v_mfma_f32_16x16x32_bf16 v[32:35], v[136:139], v[190:193], v[32:35]
	v_mfma_f32_16x16x32_bf16 v[28:31], v[144:147], v[190:193], v[28:31]
	v_mfma_f32_16x16x32_bf16 v[24:27], v[194:197], v[148:151], v[24:27]
	v_mfma_f32_16x16x32_bf16 v[20:23], v[202:205], v[148:151], v[20:23]
	v_mfma_f32_16x16x32_bf16 v[16:19], v[194:197], v[156:159], v[16:19]
	v_mfma_f32_16x16x32_bf16 v[12:15], v[202:205], v[156:159], v[12:15]
	v_mfma_f32_16x16x32_bf16 v[8:11], v[194:197], v[164:167], v[8:11]
	v_mfma_f32_16x16x32_bf16 v[4:7], v[202:205], v[164:167], v[4:7]
	v_mfma_f32_16x16x32_bf16 v[60:63], v[194:197], v[186:189], v[60:63]
	v_mfma_f32_16x16x32_bf16 v[64:67], v[202:205], v[186:189], v[64:67]
	v_mfma_f32_16x16x32_bf16 v[24:27], v[198:201], v[152:155], v[24:27]
	v_mfma_f32_16x16x32_bf16 v[20:23], v[208:211], v[152:155], v[20:23]
	v_mfma_f32_16x16x32_bf16 v[16:19], v[198:201], v[160:163], v[16:19]
	v_mfma_f32_16x16x32_bf16 v[12:15], v[208:211], v[160:163], v[12:15]
	v_mfma_f32_16x16x32_bf16 v[8:11], v[198:201], v[168:171], v[8:11]
	v_mfma_f32_16x16x32_bf16 v[4:7], v[208:211], v[168:171], v[4:7]
	v_mfma_f32_16x16x32_bf16 v[60:63], v[198:201], v[190:193], v[60:63]
	v_mfma_f32_16x16x32_bf16 v[64:67], v[208:211], v[190:193], v[64:67]
	s_barrier
	s_cbranch_scc0 .LBB0_1526
	s_setprio 0
	v_bfe_u32 v186, v0, 4, 2
	s_lshl_b32 s4, s53, 7
	s_or_b32 s4, s4, s29
	v_lshl_or_b32 v186, v186, 3, s4
	v_lshlrev_b32_e32 v186, 2, v186
	global_load_dwordx4 v[162:165], v186, s[36:37] offset:16
	global_load_dwordx4 v[170:173], v186, s[36:37]
	global_load_dwordx4 v[154:157], v186, s[48:49] offset:16
	global_load_dwordx4 v[166:169], v186, s[48:49]
	global_load_dwordx4 v[146:149], v186, s[50:51] offset:16
	global_load_dwordx4 v[158:161], v186, s[50:51]
	global_load_dwordx4 v[142:145], v186, s[42:43] offset:16
	global_load_dwordx4 v[150:153], v186, s[42:43]
	s_lshl_b32 s4, s66, 10
	v_mov_b32_e32 v134, v0
	s_and_b32 s4, s4, 0x400
	s_add_i32 s4, s35, s4
	v_and_b32_e32 v210, 15, v134
	v_lshl_add_u32 v2, v210, 2, s4
	ds_read2_b32 v[204:205], v2 offset1:16
	ds_read2_b32 v[202:203], v2 offset0:32 offset1:48
	ds_read2_b32 v[198:199], v2 offset0:128 offset1:144
	ds_read2_b32 v[196:197], v2 offset0:160 offset1:176
	v_cmp_lt_u32_e32 vcc, 13, v210
	s_waitcnt lgkmcnt(0)
	v_mov_b32_e32 v206, v205
	v_mov_b32_e32 v208, v203
	v_mov_b32_e32 v2, v199
	v_mov_b32_e32 v200, v197
	v_pk_mul_f32 v[132:133], v[130:131], v[208:209] op_sel_hi:[1,0]
	v_pk_mul_f32 v[130:131], v[128:129], v[208:209] op_sel_hi:[1,0]
	v_pk_mul_f32 v[128:129], v[126:127], v[208:209] op_sel_hi:[1,0]
	v_pk_mul_f32 v[126:127], v[124:125], v[208:209] op_sel_hi:[1,0]
	v_pk_mul_f32 v[62:63], v[62:63], v[200:201] op_sel_hi:[1,0]
	v_pk_mul_f32 v[60:61], v[60:61], v[200:201] op_sel_hi:[1,0]
	v_pk_mul_f32 v[66:67], v[66:67], v[200:201] op_sel_hi:[1,0]
	v_pk_mul_f32 v[64:65], v[64:65], v[200:201] op_sel_hi:[1,0]
	v_bfe_u32 v125, v134, 4, 2
	s_and_saveexec_b64 s[4:5], vcc
	s_cbranch_execz .LBB0_1529
	v_lshlrev_b32_e32 v124, 1, v125
	v_add3_u32 v124, v210, v124, -14
	v_add_u32_e32 v134, s39, v124
	v_add_u32_e32 v124, s38, v124
	v_lshl_add_u32 v124, v124, 5, s62
	v_lshl_add_u32 v134, v134, 5, s62
	ds_write_b128 v124, v[130:133]
	ds_write_b128 v124, v[126:129] offset:16
	ds_write_b128 v134, v[60:63]
	ds_write_b128 v134, v[64:67] offset:16
.LBB0_1529:
	s_or_b64 exec, exec, s[4:5]
	s_lshl_b32 s4, s53, 7
	s_or_b32 s4, s4, s29
	v_lshl_or_b32 v188, v125, 3, s4
	v_ashrrev_i32_e32 v189, 31, v188
	v_lshlrev_b64 v[186:187], 2, v[188:189]
	s_waitcnt lgkmcnt(0)
	s_barrier
	s_barrier
	s_and_b64 s[6:7], s[44:45], vcc
	v_mov_b32_e32 v124, 0
	v_lshlrev_b32_e32 v197, 6, v125
	v_lshlrev_b32_e32 v199, 5, v210
	v_mov_b32_e32 v134, 0
	v_mov_b32_e32 v135, 0
	v_mov_b32_e32 v136, 0
	v_mov_b32_e32 v137, 0
	v_mov_b32_e32 v138, 0
	v_mov_b32_e32 v139, 0
	v_mov_b32_e32 v140, 0
	v_mov_b32_e32 v141, 0
	s_and_saveexec_b64 s[4:5], s[6:7]
	s_cbranch_execz .LBB0_1531
	v_add3_u32 v125, s63, v197, v199
	v_add_u32_e32 v134, 0xfffffe50, v125
	v_add_u32_e32 v125, 0xfffffe40, v125
	ds_read_b128 v[138:141], v125
	ds_read_b128 v[134:137], v134
